# v11 + seam barrier thread issues its CU's L1 invalidate at arrival (overlapped with the wait) instead of after the release
# baseline (speedup 1.0000x reference)
; __device__ __forceinline__ unsigned xb_ld(unsigned* p)              { return __hip_atomic_load(p, __ATOMIC_RELAXED, __HIP_MEMORY_SCOPE_AGENT); }
; __device__ __forceinline__ void xcd_barrier_complete(unsigned* bar, unsigned x, unsigned& nloc, unsigned& nx) {
;     const unsigned G = gridDim.x * gridDim.y * gridDim.z;
;     unsigned sum, cnt, mine, sp = 0u;
;     for (;;) {
;         sum = 0u; cnt = 0u; mine = 0u;
; #pragma unroll
;         for (unsigned j = 0; j < 16; ++j) { const unsigned c = xb_ld(&bar[XB_XCNT(j)]); sum += c; cnt += (c > 0u) ? 1u : 0u; mine = (j == x) ? c : mine; }
; __device__ __forceinline__ void xcd_barrier(const XcdBarrier& b) {
;     asm volatile("s_waitcnt vmcnt(0)" ::: "memory");
;     __syncthreads();
;     if (threadIdx.x == 0) {
;         unsigned* bar = b.bar;
;         __builtin_amdgcn_s_waitcnt(0);
;         unsigned nloc = b.st[0], nx = b.st[1];
;         if (nloc == 0u) { xcd_barrier_complete(bar, b.x, nloc, nx); b.st[0] = nloc; b.st[1] = nx; }
.LBB0_175:
	s_load_dwordx2 s[0:1], s[88:89], 0xa0
	s_waitcnt lgkmcnt(0)
	s_cmp_gt_i32 s1, 1
	s_cselect_b64 s[16:17], -1, 0
	s_and_b64 s[0:1], s[14:15], s[16:17]
	s_andn2_b64 vcc, exec, s[0:1]
	s_cbranch_vccnz .LBB0_229
	s_waitcnt vmcnt(0)
	s_barrier
	s_mov_b64 s[2:3], exec
	v_readlane_b32 s4, v247, 1
	v_readlane_b32 s5, v247, 2
	s_and_b64 s[4:5], s[2:3], s[4:5]
	s_mov_b64 exec, s[4:5]
	s_cbranch_execz .LBB0_228
	s_add_i32 s4, 0, 0x23fc0
	v_mov_b32_e32 v0, s4
	s_waitcnt vmcnt(0) expcnt(0) lgkmcnt(0)
	buffer_inv sc1
	ds_read_b32 v2, v0
	s_add_i32 s4, 0, 0x23fc4
	v_mov_b32_e32 v0, s4
	ds_read_b32 v0, v0
	s_waitcnt lgkmcnt(1)
	v_cmp_ne_u32_e32 vcc, 0, v2
	s_cbranch_vccnz .LBB0_192
	s_load_dword s4, s[88:89], 0xb0
	s_mov_b32 s50, 1
	v_mov_b32_e32 v16, 0
	s_waitcnt lgkmcnt(0)
	s_mul_i32 s33, s4, s86
	s_add_u32 s4, s92, 0x288c200
	s_addc_u32 s5, s93, 0
	s_add_u32 s6, s92, 0x288c400
	s_addc_u32 s7, s93, 0
	s_add_u32 s8, s92, 0x288c500
	s_addc_u32 s9, s93, 0
	s_add_u32 s10, s92, 0x288c600
	s_addc_u32 s11, s93, 0
	s_add_u32 s14, s92, 0x288c700
	s_addc_u32 s15, s93, 0
	s_add_u32 s18, s92, 0x288c800
	s_addc_u32 s19, s93, 0
	s_add_u32 s20, s92, 0x288c900
	s_addc_u32 s21, s93, 0
	s_add_u32 s22, s92, 0x288ca00
	s_addc_u32 s23, s93, 0
	s_add_u32 s24, s92, 0x288cb00
	s_addc_u32 s25, s93, 0
	s_add_u32 s26, s92, 0x288cc00
	s_addc_u32 s27, s93, 0
	s_add_u32 s28, s92, 0x288cd00
	s_addc_u32 s29, s93, 0
	s_add_u32 s30, s92, 0x288ce00
	s_addc_u32 s31, s93, 0
	s_add_u32 s34, s92, 0x288cf00
	s_addc_u32 s35, s93, 0
	s_add_u32 s36, s92, 0x288d000
	s_addc_u32 s37, s93, 0
	s_add_u32 s38, s92, 0x288d100
	s_addc_u32 s39, s93, 0
	s_add_u32 s40, s92, 0x288d200
	s_addc_u32 s41, s93, 0
	s_add_u32 s42, s92, 0x288d300
	s_mul_i32 s33, s33, s87
	s_addc_u32 s43, s93, 0
	s_branch .LBB0_180

; __device__ __forceinline__ unsigned xb_ld(unsigned* p)              { return __hip_atomic_load(p, __ATOMIC_RELAXED, __HIP_MEMORY_SCOPE_AGENT); }
; #define XB_SPIN(cond, bar) do { unsigned _sp = 0; while (cond) { __builtin_amdgcn_s_sleep(1); \
;     if ((++_sp & 255u) == 0u) { if (xb_ld(&(bar)[XB_TMO])) break; if (_sp > XB_SPIN_CAP) { atomicAdd(&(bar)[XB_TMO], 1u); break; } } } } while (0)
; __device__ __forceinline__ void xcd_barrier(const XcdBarrier& b) {
;     ...
;             XB_SPIN(xb_ld(&bar[XB_XGEN(b.x)]) == gen, bar);
;             __builtin_amdgcn_fence(__ATOMIC_ACQUIRE, "agent");
;             asm volatile("s_waitcnt vmcnt(0)" ::: "memory");
.LBB0_207:
	s_or_b64 exec, exec, s[8:9]
	s_waitcnt vmcnt(0)
	s_waitcnt vmcnt(0)

; __device__ __forceinline__ unsigned xb_ld(unsigned* p)              { return __hip_atomic_load(p, __ATOMIC_RELAXED, __HIP_MEMORY_SCOPE_AGENT); }
; __device__ __forceinline__ unsigned xb_add(unsigned* p, unsigned v) { return __hip_atomic_fetch_add(p, v, __ATOMIC_RELAXED, __HIP_MEMORY_SCOPE_AGENT); }
; #define XB_SPIN(cond, bar) do { unsigned _sp = 0; while (cond) { __builtin_amdgcn_s_sleep(1); \
;     if ((++_sp & 255u) == 0u) { if (xb_ld(&(bar)[XB_TMO])) break; if (_sp > XB_SPIN_CAP) { atomicAdd(&(bar)[XB_TMO], 1u); break; } } } } while (0)
; __device__ __forceinline__ void xcd_barrier(const XcdBarrier& b) {
;     ...
;             else XB_SPIN(xb_ld(&bar[XB_TOPGEN]) == tg, bar);
;             __builtin_amdgcn_fence(__ATOMIC_ACQUIRE, "agent");
;             xb_add(&bar[XB_XGEN(b.x)], 1u);
.LBB0_225:
	s_or_b64 exec, exec, s[6:7]
	s_mov_b64 s[6:7], exec
	v_mbcnt_lo_u32_b32 v0, s6, 0
	v_mbcnt_hi_u32_b32 v0, s7, v0
	v_cmp_eq_u32_e32 vcc, 0, v0
	s_waitcnt vmcnt(0)
	s_and_saveexec_b64 s[8:9], vcc
	s_cbranch_execz .LBB0_227
	s_bcnt1_i32_b64 s6, s[6:7]
	v_mov_b32_e32 v0, 0x2000
	v_mov_b32_e32 v1, s6
	global_atomic_add v0, v1, s[4:5] offset:1024

; __device__ __forceinline__ unsigned xb_ld(unsigned* p)              { return __hip_atomic_load(p, __ATOMIC_RELAXED, __HIP_MEMORY_SCOPE_AGENT); }
; __device__ __forceinline__ void xcd_barrier_complete(unsigned* bar, unsigned x, unsigned& nloc, unsigned& nx) {
;     const unsigned G = gridDim.x * gridDim.y * gridDim.z;
;     unsigned sum, cnt, mine, sp = 0u;
;     for (;;) {
;         sum = 0u; cnt = 0u; mine = 0u;
; #pragma unroll
;         for (unsigned j = 0; j < 16; ++j) { const unsigned c = xb_ld(&bar[XB_XCNT(j)]); sum += c; cnt += (c > 0u) ? 1u : 0u; mine = (j == x) ? c : mine; }
; __device__ __forceinline__ void xcd_barrier(const XcdBarrier& b) {
;     asm volatile("s_waitcnt vmcnt(0)" ::: "memory");
;     __syncthreads();
;     if (threadIdx.x == 0) {
;         unsigned* bar = b.bar;
;         __builtin_amdgcn_s_waitcnt(0);
;         unsigned nloc = b.st[0], nx = b.st[1];
;         if (nloc == 0u) { xcd_barrier_complete(bar, b.x, nloc, nx); b.st[0] = nloc; b.st[1] = nx; }
.LBB0_251:
	s_load_dwordx2 s[0:1], s[88:89], 0xa0
	s_waitcnt lgkmcnt(0)
	s_cmp_gt_i32 s1, 2
	s_cselect_b64 s[0:1], -1, 0
	s_and_b64 s[2:3], s[2:3], s[0:1]
	s_andn2_b64 vcc, exec, s[2:3]
	s_cbranch_vccnz .LBB0_305
	s_waitcnt vmcnt(0)
	s_waitcnt vmcnt(0)
	s_barrier
	s_mov_b64 s[2:3], exec
	v_readlane_b32 s4, v247, 1
	v_readlane_b32 s5, v247, 2
	s_and_b64 s[4:5], s[2:3], s[4:5]
	s_mov_b64 exec, s[4:5]
	s_cbranch_execz .LBB0_304
	s_add_i32 s4, 0, 0x23fc0
	v_mov_b32_e32 v0, s4
	s_waitcnt vmcnt(0) expcnt(0) lgkmcnt(0)
	buffer_inv sc1
	ds_read_b32 v2, v0
	s_add_i32 s4, 0, 0x23fc4
	v_mov_b32_e32 v0, s4
	ds_read_b32 v0, v0
	s_waitcnt lgkmcnt(1)
	v_cmp_ne_u32_e32 vcc, 0, v2
	s_cbranch_vccnz .LBB0_268
	s_load_dword s4, s[88:89], 0xb0
	s_mov_b32 s51, 1
	v_mov_b32_e32 v16, 0
	s_waitcnt lgkmcnt(0)
	s_mul_i32 s50, s4, s86
	s_add_u32 s4, s92, 0x288c200
	s_addc_u32 s5, s93, 0
	s_add_u32 s6, s92, 0x288c400
	s_addc_u32 s7, s93, 0
	s_add_u32 s8, s92, 0x288c500
	s_addc_u32 s9, s93, 0
	s_add_u32 s10, s92, 0x288c600
	s_addc_u32 s11, s93, 0
	s_add_u32 s12, s92, 0x288c700
	s_addc_u32 s13, s93, 0
	s_add_u32 s14, s92, 0x288c800
	s_addc_u32 s15, s93, 0
	s_add_u32 s16, s92, 0x288c900
	s_addc_u32 s17, s93, 0
	s_add_u32 s18, s92, 0x288ca00
	s_addc_u32 s19, s93, 0
	s_add_u32 s20, s92, 0x288cb00
	s_addc_u32 s21, s93, 0
	s_add_u32 s22, s92, 0x288cc00
	s_addc_u32 s23, s93, 0
	s_add_u32 s24, s92, 0x288cd00
	s_addc_u32 s25, s93, 0
	s_add_u32 s26, s92, 0x288ce00
	s_addc_u32 s27, s93, 0
	s_add_u32 s28, s92, 0x288cf00
	s_addc_u32 s29, s93, 0
	s_add_u32 s30, s92, 0x288d000
	s_addc_u32 s31, s93, 0
	s_add_u32 s34, s92, 0x288d100
	s_addc_u32 s35, s93, 0
	s_add_u32 s36, s92, 0x288d200
	s_addc_u32 s37, s93, 0
	s_add_u32 s38, s92, 0x288d300
	s_mul_i32 s50, s50, s87
	s_addc_u32 s39, s93, 0
	s_branch .LBB0_256

; __device__ __forceinline__ unsigned xb_ld(unsigned* p)              { return __hip_atomic_load(p, __ATOMIC_RELAXED, __HIP_MEMORY_SCOPE_AGENT); }
; __device__ __forceinline__ void xcd_barrier_complete(unsigned* bar, unsigned x, unsigned& nloc, unsigned& nx) {
;     const unsigned G = gridDim.x * gridDim.y * gridDim.z;
;     unsigned sum, cnt, mine, sp = 0u;
;     for (;;) {
;         sum = 0u; cnt = 0u; mine = 0u;
; #pragma unroll
;         for (unsigned j = 0; j < 16; ++j) { const unsigned c = xb_ld(&bar[XB_XCNT(j)]); sum += c; cnt += (c > 0u) ? 1u : 0u; mine = (j == x) ? c : mine; }
; __device__ __forceinline__ void xcd_barrier(const XcdBarrier& b) {
;     asm volatile("s_waitcnt vmcnt(0)" ::: "memory");
;     __syncthreads();
;     if (threadIdx.x == 0) {
;         unsigned* bar = b.bar;
;         __builtin_amdgcn_s_waitcnt(0);
;         unsigned nloc = b.st[0], nx = b.st[1];
;         if (nloc == 0u) { xcd_barrier_complete(bar, b.x, nloc, nx); b.st[0] = nloc; b.st[1] = nx; }
.LBB0_344:
	s_load_dwordx2 s[0:1], s[88:89], 0xa0
	s_waitcnt lgkmcnt(0)
	s_cmp_gt_i32 s1, 3
	s_cselect_b64 s[0:1], -1, 0
	s_and_b64 s[2:3], s[6:7], s[0:1]
	s_andn2_b64 vcc, exec, s[2:3]
	s_cbranch_vccnz .LBB0_398
	s_waitcnt vmcnt(0)
	s_waitcnt vmcnt(0)
	s_barrier
	s_mov_b64 s[2:3], exec
	v_readlane_b32 s4, v247, 1
	v_readlane_b32 s5, v247, 2
	s_and_b64 s[4:5], s[2:3], s[4:5]
	s_mov_b64 exec, s[4:5]
	s_cbranch_execz .LBB0_397
	s_add_i32 s4, 0, 0x23fc0
	v_mov_b32_e32 v0, s4
	s_waitcnt vmcnt(0) expcnt(0) lgkmcnt(0)
	buffer_inv sc1
	ds_read_b32 v2, v0
	s_add_i32 s4, 0, 0x23fc4
	v_mov_b32_e32 v0, s4
	ds_read_b32 v0, v0
	s_waitcnt lgkmcnt(1)
	v_cmp_ne_u32_e32 vcc, 0, v2
	s_cbranch_vccnz .LBB0_361
	s_load_dword s4, s[88:89], 0xb0
	s_mov_b32 s53, 1
	v_mov_b32_e32 v16, 0
	s_waitcnt lgkmcnt(0)
	s_mul_i32 s52, s4, s86
	s_add_u32 s4, s92, 0x288c200
	s_addc_u32 s5, s93, 0
	s_add_u32 s6, s92, 0x288c400
	s_addc_u32 s7, s93, 0
	s_add_u32 s8, s92, 0x288c500
	s_addc_u32 s9, s93, 0
	s_add_u32 s10, s92, 0x288c600
	s_addc_u32 s11, s93, 0
	s_add_u32 s12, s92, 0x288c700
	s_addc_u32 s13, s93, 0
	s_add_u32 s14, s92, 0x288c800
	s_addc_u32 s15, s93, 0
	s_add_u32 s16, s92, 0x288c900
	s_addc_u32 s17, s93, 0
	s_add_u32 s18, s92, 0x288ca00
	s_addc_u32 s19, s93, 0
	s_add_u32 s20, s92, 0x288cb00
	s_addc_u32 s21, s93, 0
	s_add_u32 s22, s92, 0x288cc00
	s_addc_u32 s23, s93, 0
	s_add_u32 s24, s92, 0x288cd00
	s_addc_u32 s25, s93, 0
	s_add_u32 s26, s92, 0x288ce00
	s_addc_u32 s27, s93, 0
	s_add_u32 s28, s92, 0x288cf00
	s_addc_u32 s29, s93, 0
	s_add_u32 s30, s92, 0x288d000
	s_addc_u32 s31, s93, 0
	s_add_u32 s34, s92, 0x288d100
	s_addc_u32 s35, s93, 0
	s_add_u32 s36, s92, 0x288d200
	s_addc_u32 s37, s93, 0
	s_add_u32 s38, s92, 0x288d300
	s_mul_i32 s52, s52, s87
	s_addc_u32 s39, s93, 0
	s_branch .LBB0_349

; __device__ __forceinline__ unsigned xb_ld(unsigned* p)              { return __hip_atomic_load(p, __ATOMIC_RELAXED, __HIP_MEMORY_SCOPE_AGENT); }
; __device__ __forceinline__ void xcd_barrier_complete(unsigned* bar, unsigned x, unsigned& nloc, unsigned& nx) {
;     const unsigned G = gridDim.x * gridDim.y * gridDim.z;
;     unsigned sum, cnt, mine, sp = 0u;
;     for (;;) {
;         sum = 0u; cnt = 0u; mine = 0u;
; #pragma unroll
;         for (unsigned j = 0; j < 16; ++j) { const unsigned c = xb_ld(&bar[XB_XCNT(j)]); sum += c; cnt += (c > 0u) ? 1u : 0u; mine = (j == x) ? c : mine; }
; __device__ __forceinline__ void xcd_barrier(const XcdBarrier& b) {
;     asm volatile("s_waitcnt vmcnt(0)" ::: "memory");
;     __syncthreads();
;     if (threadIdx.x == 0) {
;         unsigned* bar = b.bar;
;         __builtin_amdgcn_s_waitcnt(0);
;         unsigned nloc = b.st[0], nx = b.st[1];
;         if (nloc == 0u) { xcd_barrier_complete(bar, b.x, nloc, nx); b.st[0] = nloc; b.st[1] = nx; }
.LBB0_481:
	s_load_dwordx2 s[0:1], s[88:89], 0xa0
	s_waitcnt lgkmcnt(0)
	s_cmp_gt_i32 s1, 4
	s_cselect_b64 s[0:1], -1, 0
	s_and_b64 s[2:3], s[22:23], s[0:1]
	s_andn2_b64 vcc, exec, s[2:3]
	s_cbranch_vccnz .LBB0_535
	s_waitcnt vmcnt(0)
	s_waitcnt vmcnt(0)
	s_barrier
	s_mov_b64 s[2:3], exec
	v_readlane_b32 s4, v247, 1
	v_readlane_b32 s5, v247, 2
	s_and_b64 s[4:5], s[2:3], s[4:5]
	s_mov_b64 exec, s[4:5]
	s_cbranch_execz .LBB0_534
	s_add_i32 s4, 0, 0x23fc0
	v_mov_b32_e32 v0, s4
	s_waitcnt vmcnt(0) expcnt(0) lgkmcnt(0)
	buffer_inv sc1
	ds_read_b32 v2, v0
	s_add_i32 s4, 0, 0x23fc4
	v_mov_b32_e32 v0, s4
	ds_read_b32 v0, v0
	s_waitcnt lgkmcnt(1)
	v_cmp_ne_u32_e32 vcc, 0, v2
	s_cbranch_vccnz .LBB0_498
	s_load_dword s4, s[88:89], 0xb0
	s_mov_b32 s53, 1
	v_mov_b32_e32 v16, 0
	s_waitcnt lgkmcnt(0)
	s_mul_i32 s52, s4, s86
	s_add_u32 s4, s92, 0x288c200
	s_addc_u32 s5, s93, 0
	s_add_u32 s6, s92, 0x288c400
	s_addc_u32 s7, s93, 0
	s_add_u32 s8, s92, 0x288c500
	s_addc_u32 s9, s93, 0
	s_add_u32 s10, s92, 0x288c600
	s_addc_u32 s11, s93, 0
	s_add_u32 s12, s92, 0x288c700
	s_addc_u32 s13, s93, 0
	s_add_u32 s14, s92, 0x288c800
	s_addc_u32 s15, s93, 0
	s_add_u32 s16, s92, 0x288c900
	s_addc_u32 s17, s93, 0
	s_add_u32 s18, s92, 0x288ca00
	s_addc_u32 s19, s93, 0
	s_add_u32 s20, s92, 0x288cb00
	s_addc_u32 s21, s93, 0
	s_add_u32 s22, s92, 0x288cc00
	s_addc_u32 s23, s93, 0
	s_add_u32 s24, s92, 0x288cd00
	s_addc_u32 s25, s93, 0
	s_add_u32 s26, s92, 0x288ce00
	s_addc_u32 s27, s93, 0
	s_add_u32 s28, s92, 0x288cf00
	s_addc_u32 s29, s93, 0
	s_add_u32 s30, s92, 0x288d000
	s_addc_u32 s31, s93, 0
	s_add_u32 s34, s92, 0x288d100
	s_addc_u32 s35, s93, 0
	s_add_u32 s36, s92, 0x288d200
	s_addc_u32 s37, s93, 0
	s_add_u32 s38, s92, 0x288d300
	s_mul_i32 s52, s52, s87
	s_addc_u32 s39, s93, 0
	s_branch .LBB0_486

; __device__ __forceinline__ unsigned xb_ld(unsigned* p)              { return __hip_atomic_load(p, __ATOMIC_RELAXED, __HIP_MEMORY_SCOPE_AGENT); }
; __device__ __forceinline__ void xcd_barrier_complete(unsigned* bar, unsigned x, unsigned& nloc, unsigned& nx) {
;     const unsigned G = gridDim.x * gridDim.y * gridDim.z;
;     unsigned sum, cnt, mine, sp = 0u;
;     for (;;) {
;         sum = 0u; cnt = 0u; mine = 0u;
; #pragma unroll
;         for (unsigned j = 0; j < 16; ++j) { const unsigned c = xb_ld(&bar[XB_XCNT(j)]); sum += c; cnt += (c > 0u) ? 1u : 0u; mine = (j == x) ? c : mine; }
; __device__ __forceinline__ void xcd_barrier(const XcdBarrier& b) {
;     asm volatile("s_waitcnt vmcnt(0)" ::: "memory");
;     __syncthreads();
;     if (threadIdx.x == 0) {
;         unsigned* bar = b.bar;
;         __builtin_amdgcn_s_waitcnt(0);
;         unsigned nloc = b.st[0], nx = b.st[1];
;         if (nloc == 0u) { xcd_barrier_complete(bar, b.x, nloc, nx); b.st[0] = nloc; b.st[1] = nx; }
.LBB0_579:
	s_load_dwordx2 s[0:1], s[88:89], 0xa0
	s_waitcnt lgkmcnt(0)
	s_cmp_gt_i32 s1, 5
	s_cselect_b64 s[0:1], -1, 0
	s_and_b64 s[2:3], s[4:5], s[0:1]
	s_andn2_b64 vcc, exec, s[2:3]
	s_cbranch_vccnz .LBB0_633
	s_waitcnt vmcnt(0)
	s_waitcnt vmcnt(0)
	s_barrier
	s_mov_b64 s[2:3], exec
	v_readlane_b32 s4, v247, 1
	v_readlane_b32 s5, v247, 2
	s_and_b64 s[4:5], s[2:3], s[4:5]
	s_mov_b64 exec, s[4:5]
	s_cbranch_execz .LBB0_632
	s_add_i32 s4, 0, 0x23fc0
	v_mov_b32_e32 v0, s4
	s_waitcnt vmcnt(0) expcnt(0) lgkmcnt(0)
	buffer_inv sc1
	ds_read_b32 v2, v0
	s_add_i32 s4, 0, 0x23fc4
	v_mov_b32_e32 v0, s4
	ds_read_b32 v0, v0
	s_waitcnt lgkmcnt(1)
	v_cmp_ne_u32_e32 vcc, 0, v2
	s_cbranch_vccnz .LBB0_596
	s_load_dword s4, s[88:89], 0xb0
	s_mov_b32 s53, 1
	v_mov_b32_e32 v16, 0
	s_waitcnt lgkmcnt(0)
	s_mul_i32 s52, s4, s86
	s_add_u32 s4, s92, 0x288c200
	s_addc_u32 s5, s93, 0
	s_add_u32 s6, s92, 0x288c400
	s_addc_u32 s7, s93, 0
	s_add_u32 s8, s92, 0x288c500
	s_addc_u32 s9, s93, 0
	s_add_u32 s10, s92, 0x288c600
	s_addc_u32 s11, s93, 0
	s_add_u32 s12, s92, 0x288c700
	s_addc_u32 s13, s93, 0
	s_add_u32 s14, s92, 0x288c800
	s_addc_u32 s15, s93, 0
	s_add_u32 s16, s92, 0x288c900
	s_addc_u32 s17, s93, 0
	s_add_u32 s18, s92, 0x288ca00
	s_addc_u32 s19, s93, 0
	s_add_u32 s20, s92, 0x288cb00
	s_addc_u32 s21, s93, 0
	s_add_u32 s22, s92, 0x288cc00
	s_addc_u32 s23, s93, 0
	s_add_u32 s24, s92, 0x288cd00
	s_addc_u32 s25, s93, 0
	s_add_u32 s26, s92, 0x288ce00
	s_addc_u32 s27, s93, 0
	s_add_u32 s28, s92, 0x288cf00
	s_addc_u32 s29, s93, 0
	s_add_u32 s30, s92, 0x288d000
	s_addc_u32 s31, s93, 0
	s_add_u32 s34, s92, 0x288d100
	s_addc_u32 s35, s93, 0
	s_add_u32 s36, s92, 0x288d200
	s_addc_u32 s37, s93, 0
	s_add_u32 s38, s92, 0x288d300
	s_mul_i32 s52, s52, s87
	s_addc_u32 s39, s93, 0
	s_branch .LBB0_584

; __device__ __forceinline__ unsigned xb_ld(unsigned* p)              { return __hip_atomic_load(p, __ATOMIC_RELAXED, __HIP_MEMORY_SCOPE_AGENT); }
; __device__ __forceinline__ void xcd_barrier_complete(unsigned* bar, unsigned x, unsigned& nloc, unsigned& nx) {
;     const unsigned G = gridDim.x * gridDim.y * gridDim.z;
;     unsigned sum, cnt, mine, sp = 0u;
;     for (;;) {
;         sum = 0u; cnt = 0u; mine = 0u;
; #pragma unroll
;         for (unsigned j = 0; j < 16; ++j) { const unsigned c = xb_ld(&bar[XB_XCNT(j)]); sum += c; cnt += (c > 0u) ? 1u : 0u; mine = (j == x) ? c : mine; }
; __device__ __forceinline__ void xcd_barrier(const XcdBarrier& b) {
;     asm volatile("s_waitcnt vmcnt(0)" ::: "memory");
;     __syncthreads();
;     if (threadIdx.x == 0) {
;         unsigned* bar = b.bar;
;         __builtin_amdgcn_s_waitcnt(0);
;         unsigned nloc = b.st[0], nx = b.st[1];
;         if (nloc == 0u) { xcd_barrier_complete(bar, b.x, nloc, nx); b.st[0] = nloc; b.st[1] = nx; }
.LBB0_640:
	s_load_dwordx2 s[0:1], s[88:89], 0xa0
	s_waitcnt lgkmcnt(0)
	s_cmp_gt_i32 s1, 6
	s_cselect_b64 s[0:1], -1, 0
	s_and_b64 s[2:3], s[4:5], s[0:1]
	s_andn2_b64 vcc, exec, s[2:3]
	s_cbranch_vccnz .LBB0_694
	s_waitcnt vmcnt(0)
	s_waitcnt vmcnt(0)
	s_barrier
	s_mov_b64 s[2:3], exec
	v_readlane_b32 s4, v247, 1
	v_readlane_b32 s5, v247, 2
	s_and_b64 s[4:5], s[2:3], s[4:5]
	s_mov_b64 exec, s[4:5]
	s_cbranch_execz .LBB0_693
	s_add_i32 s4, 0, 0x23fc0
	v_mov_b32_e32 v0, s4
	s_waitcnt vmcnt(0) expcnt(0) lgkmcnt(0)
	buffer_inv sc1
	ds_read_b32 v2, v0
	s_add_i32 s4, 0, 0x23fc4
	v_mov_b32_e32 v0, s4
	ds_read_b32 v0, v0
	s_waitcnt lgkmcnt(1)
	v_cmp_ne_u32_e32 vcc, 0, v2
	s_cbranch_vccnz .LBB0_657
	s_load_dword s4, s[88:89], 0xb0
	s_mov_b32 s53, 1
	v_mov_b32_e32 v16, 0
	s_waitcnt lgkmcnt(0)
	s_mul_i32 s52, s4, s86
	s_add_u32 s4, s92, 0x288c200
	s_addc_u32 s5, s93, 0
	s_add_u32 s6, s92, 0x288c400
	s_addc_u32 s7, s93, 0
	s_add_u32 s8, s92, 0x288c500
	s_addc_u32 s9, s93, 0
	s_add_u32 s10, s92, 0x288c600
	s_addc_u32 s11, s93, 0
	s_add_u32 s12, s92, 0x288c700
	s_addc_u32 s13, s93, 0
	s_add_u32 s14, s92, 0x288c800
	s_addc_u32 s15, s93, 0
	s_add_u32 s16, s92, 0x288c900
	s_addc_u32 s17, s93, 0
	s_add_u32 s18, s92, 0x288ca00
	s_addc_u32 s19, s93, 0
	s_add_u32 s20, s92, 0x288cb00
	s_addc_u32 s21, s93, 0
	s_add_u32 s22, s92, 0x288cc00
	s_addc_u32 s23, s93, 0
	s_add_u32 s24, s92, 0x288cd00
	s_addc_u32 s25, s93, 0
	s_add_u32 s26, s92, 0x288ce00
	s_addc_u32 s27, s93, 0
	s_add_u32 s28, s92, 0x288cf00
	s_addc_u32 s29, s93, 0
	s_add_u32 s30, s92, 0x288d000
	s_addc_u32 s31, s93, 0
	s_add_u32 s34, s92, 0x288d100
	s_addc_u32 s35, s93, 0
	s_add_u32 s36, s92, 0x288d200
	s_addc_u32 s37, s93, 0
	s_add_u32 s38, s92, 0x288d300
	s_mul_i32 s52, s52, s87
	s_addc_u32 s39, s93, 0
	s_branch .LBB0_645

; __device__ __forceinline__ unsigned xb_ld(unsigned* p)              { return __hip_atomic_load(p, __ATOMIC_RELAXED, __HIP_MEMORY_SCOPE_AGENT); }
; __device__ __forceinline__ void xcd_barrier_complete(unsigned* bar, unsigned x, unsigned& nloc, unsigned& nx) {
;     const unsigned G = gridDim.x * gridDim.y * gridDim.z;
;     unsigned sum, cnt, mine, sp = 0u;
;     for (;;) {
;         sum = 0u; cnt = 0u; mine = 0u;
; #pragma unroll
;         for (unsigned j = 0; j < 16; ++j) { const unsigned c = xb_ld(&bar[XB_XCNT(j)]); sum += c; cnt += (c > 0u) ? 1u : 0u; mine = (j == x) ? c : mine; }
; __device__ __forceinline__ void xcd_barrier(const XcdBarrier& b) {
;     asm volatile("s_waitcnt vmcnt(0)" ::: "memory");
;     __syncthreads();
;     if (threadIdx.x == 0) {
;         unsigned* bar = b.bar;
;         __builtin_amdgcn_s_waitcnt(0);
;         unsigned nloc = b.st[0], nx = b.st[1];
;         if (nloc == 0u) { xcd_barrier_complete(bar, b.x, nloc, nx); b.st[0] = nloc; b.st[1] = nx; }
.LBB0_703:
	v_readlane_b32 s0, v247, 4
	v_readlane_b32 s1, v247, 5
	s_cmp_gt_i32 s1, 7
	v_readlane_b32 s2, v247, 8
	s_cselect_b64 s[0:1], -1, 0
	v_readlane_b32 s3, v247, 9
	s_and_b64 s[2:3], s[2:3], s[0:1]
	s_andn2_b64 vcc, exec, s[2:3]
	s_cbranch_vccnz .LBB0_757
	s_waitcnt vmcnt(0)
	s_waitcnt vmcnt(0) lgkmcnt(0)
	s_barrier
	s_mov_b64 s[2:3], exec
	v_readlane_b32 s4, v247, 1
	v_readlane_b32 s5, v247, 2
	s_and_b64 s[4:5], s[2:3], s[4:5]
	s_mov_b64 exec, s[4:5]
	s_cbranch_execz .LBB0_756
	s_add_i32 s4, 0, 0x23fc0
	v_mov_b32_e32 v0, s4
	s_waitcnt vmcnt(0) expcnt(0) lgkmcnt(0)
	buffer_inv sc1
	ds_read_b32 v2, v0
	s_add_i32 s4, 0, 0x23fc4
	v_mov_b32_e32 v0, s4
	ds_read_b32 v0, v0
	s_waitcnt lgkmcnt(1)
	v_cmp_ne_u32_e32 vcc, 0, v2
	s_cbranch_vccnz .LBB0_720
	v_readlane_b32 s4, v247, 0
	s_mul_i32 s52, s4, s86
	s_add_u32 s4, s92, 0x288c200
	s_addc_u32 s5, s93, 0
	s_add_u32 s6, s92, 0x288c400
	s_addc_u32 s7, s93, 0
	s_add_u32 s8, s92, 0x288c500
	s_addc_u32 s9, s93, 0
	s_add_u32 s10, s92, 0x288c600
	s_addc_u32 s11, s93, 0
	s_add_u32 s12, s92, 0x288c700
	s_addc_u32 s13, s93, 0
	s_add_u32 s14, s92, 0x288c800
	s_addc_u32 s15, s93, 0
	s_add_u32 s16, s92, 0x288c900
	s_addc_u32 s17, s93, 0
	s_add_u32 s18, s92, 0x288ca00
	s_addc_u32 s19, s93, 0
	s_add_u32 s20, s92, 0x288cb00
	s_addc_u32 s21, s93, 0
	s_add_u32 s22, s92, 0x288cc00
	s_addc_u32 s23, s93, 0
	s_add_u32 s24, s92, 0x288cd00
	s_addc_u32 s25, s93, 0
	s_add_u32 s26, s92, 0x288ce00
	s_addc_u32 s27, s93, 0
	s_add_u32 s28, s92, 0x288cf00
	s_addc_u32 s29, s93, 0
	s_add_u32 s30, s92, 0x288d000
	s_addc_u32 s31, s93, 0
	s_add_u32 s34, s92, 0x288d100
	s_addc_u32 s35, s93, 0
	s_add_u32 s36, s92, 0x288d200
	s_addc_u32 s37, s93, 0
	s_add_u32 s38, s92, 0x288d300
	s_mul_i32 s52, s52, s87
	s_addc_u32 s39, s93, 0
	s_mov_b32 s53, 1
	v_mov_b32_e32 v16, 0
	s_branch .LBB0_708

; __device__ __forceinline__ unsigned xb_ld(unsigned* p)              { return __hip_atomic_load(p, __ATOMIC_RELAXED, __HIP_MEMORY_SCOPE_AGENT); }
; __device__ __forceinline__ void xcd_barrier_complete(unsigned* bar, unsigned x, unsigned& nloc, unsigned& nx) {
;     const unsigned G = gridDim.x * gridDim.y * gridDim.z;
;     unsigned sum, cnt, mine, sp = 0u;
;     for (;;) {
;         sum = 0u; cnt = 0u; mine = 0u;
; #pragma unroll
;         for (unsigned j = 0; j < 16; ++j) { const unsigned c = xb_ld(&bar[XB_XCNT(j)]); sum += c; cnt += (c > 0u) ? 1u : 0u; mine = (j == x) ? c : mine; }
; __device__ __forceinline__ void xcd_barrier(const XcdBarrier& b) {
;     asm volatile("s_waitcnt vmcnt(0)" ::: "memory");
;     __syncthreads();
;     if (threadIdx.x == 0) {
;         unsigned* bar = b.bar;
;         __builtin_amdgcn_s_waitcnt(0);
;         unsigned nloc = b.st[0], nx = b.st[1];
;         if (nloc == 0u) { xcd_barrier_complete(bar, b.x, nloc, nx); b.st[0] = nloc; b.st[1] = nx; }
.LBB0_792:
	v_readlane_b32 s0, v247, 4
	v_readlane_b32 s1, v247, 5
	s_cmp_gt_i32 s1, 8
	s_cselect_b64 s[0:1], -1, 0
	s_and_b64 s[2:3], s[4:5], s[0:1]
	s_andn2_b64 vcc, exec, s[2:3]
	s_cbranch_vccnz .LBB0_846
	s_waitcnt vmcnt(0)
	s_waitcnt vmcnt(0) lgkmcnt(0)
	s_barrier
	s_mov_b64 s[2:3], exec
	v_readlane_b32 s4, v247, 1
	v_readlane_b32 s5, v247, 2
	s_and_b64 s[4:5], s[2:3], s[4:5]
	s_mov_b64 exec, s[4:5]
	s_cbranch_execz .LBB0_845
	s_add_i32 s4, 0, 0x23fc0
	v_mov_b32_e32 v0, s4
	s_waitcnt vmcnt(0) expcnt(0) lgkmcnt(0)
	buffer_inv sc1
	ds_read_b32 v2, v0
	s_add_i32 s4, 0, 0x23fc4
	v_mov_b32_e32 v0, s4
	ds_read_b32 v0, v0
	s_waitcnt lgkmcnt(1)
	v_cmp_ne_u32_e32 vcc, 0, v2
	s_cbranch_vccnz .LBB0_809
	v_readlane_b32 s4, v247, 0
	s_mul_i32 s52, s4, s86
	s_add_u32 s4, s92, 0x288c200
	s_addc_u32 s5, s93, 0
	s_add_u32 s6, s92, 0x288c400
	s_addc_u32 s7, s93, 0
	s_add_u32 s8, s92, 0x288c500
	s_addc_u32 s9, s93, 0
	s_add_u32 s10, s92, 0x288c600
	s_addc_u32 s11, s93, 0
	s_add_u32 s12, s92, 0x288c700
	s_addc_u32 s13, s93, 0
	s_add_u32 s14, s92, 0x288c800
	s_addc_u32 s15, s93, 0
	s_add_u32 s16, s92, 0x288c900
	s_addc_u32 s17, s93, 0
	s_add_u32 s18, s92, 0x288ca00
	s_addc_u32 s19, s93, 0
	s_add_u32 s20, s92, 0x288cb00
	s_addc_u32 s21, s93, 0
	s_add_u32 s22, s92, 0x288cc00
	s_addc_u32 s23, s93, 0
	s_add_u32 s24, s92, 0x288cd00
	s_addc_u32 s25, s93, 0
	s_add_u32 s26, s92, 0x288ce00
	s_addc_u32 s27, s93, 0
	s_add_u32 s28, s92, 0x288cf00
	s_addc_u32 s29, s93, 0
	s_add_u32 s30, s92, 0x288d000
	s_addc_u32 s31, s93, 0
	s_add_u32 s34, s92, 0x288d100
	s_addc_u32 s35, s93, 0
	s_add_u32 s36, s92, 0x288d200
	s_addc_u32 s37, s93, 0
	s_add_u32 s38, s92, 0x288d300
	s_mul_i32 s52, s52, s87
	s_addc_u32 s39, s93, 0
	s_mov_b32 s53, 1
	v_mov_b32_e32 v16, 0
	s_branch .LBB0_797

; __device__ __forceinline__ unsigned xb_ld(unsigned* p)              { return __hip_atomic_load(p, __ATOMIC_RELAXED, __HIP_MEMORY_SCOPE_AGENT); }
; __device__ __forceinline__ void xcd_barrier_complete(unsigned* bar, unsigned x, unsigned& nloc, unsigned& nx) {
;     const unsigned G = gridDim.x * gridDim.y * gridDim.z;
;     unsigned sum, cnt, mine, sp = 0u;
;     for (;;) {
;         sum = 0u; cnt = 0u; mine = 0u;
; #pragma unroll
;         for (unsigned j = 0; j < 16; ++j) { const unsigned c = xb_ld(&bar[XB_XCNT(j)]); sum += c; cnt += (c > 0u) ? 1u : 0u; mine = (j == x) ? c : mine; }
; __device__ __forceinline__ void xcd_barrier(const XcdBarrier& b) {
;     asm volatile("s_waitcnt vmcnt(0)" ::: "memory");
;     __syncthreads();
;     if (threadIdx.x == 0) {
;         unsigned* bar = b.bar;
;         __builtin_amdgcn_s_waitcnt(0);
;         unsigned nloc = b.st[0], nx = b.st[1];
;         if (nloc == 0u) { xcd_barrier_complete(bar, b.x, nloc, nx); b.st[0] = nloc; b.st[1] = nx; }
.LBB0_863:
	v_readlane_b32 s0, v247, 4
	v_readlane_b32 s1, v247, 5
	s_cmp_gt_i32 s1, 9
	s_cselect_b64 s[0:1], -1, 0
	s_and_b64 s[2:3], s[2:3], s[0:1]
	s_andn2_b64 vcc, exec, s[2:3]
	s_cbranch_vccnz .LBB0_917
	s_waitcnt vmcnt(0)
	s_waitcnt vmcnt(0) lgkmcnt(0)
	s_barrier
	s_mov_b64 s[2:3], exec
	v_readlane_b32 s4, v247, 1
	v_readlane_b32 s5, v247, 2
	s_and_b64 s[4:5], s[2:3], s[4:5]
	s_mov_b64 exec, s[4:5]
	s_cbranch_execz .LBB0_916
	s_add_i32 s4, 0, 0x23fc0
	v_mov_b32_e32 v0, s4
	s_waitcnt vmcnt(0) expcnt(0) lgkmcnt(0)
	buffer_inv sc1
	ds_read_b32 v2, v0
	s_add_i32 s4, 0, 0x23fc4
	v_mov_b32_e32 v0, s4
	ds_read_b32 v0, v0
	s_waitcnt lgkmcnt(1)
	v_cmp_ne_u32_e32 vcc, 0, v2
	s_cbranch_vccnz .LBB0_880
	v_readlane_b32 s4, v247, 0
	s_mul_i32 s52, s4, s86
	s_add_u32 s4, s92, 0x288c200
	s_addc_u32 s5, s93, 0
	s_add_u32 s6, s92, 0x288c400
	s_addc_u32 s7, s93, 0
	s_add_u32 s8, s92, 0x288c500
	s_addc_u32 s9, s93, 0
	s_add_u32 s10, s92, 0x288c600
	s_addc_u32 s11, s93, 0
	s_add_u32 s12, s92, 0x288c700
	s_addc_u32 s13, s93, 0
	s_add_u32 s14, s92, 0x288c800
	s_addc_u32 s15, s93, 0
	s_add_u32 s16, s92, 0x288c900
	s_addc_u32 s17, s93, 0
	s_add_u32 s18, s92, 0x288ca00
	s_addc_u32 s19, s93, 0
	s_add_u32 s20, s92, 0x288cb00
	s_addc_u32 s21, s93, 0
	s_add_u32 s22, s92, 0x288cc00
	s_addc_u32 s23, s93, 0
	s_add_u32 s24, s92, 0x288cd00
	s_addc_u32 s25, s93, 0
	s_add_u32 s26, s92, 0x288ce00
	s_addc_u32 s27, s93, 0
	s_add_u32 s28, s92, 0x288cf00
	s_addc_u32 s29, s93, 0
	s_add_u32 s30, s92, 0x288d000
	s_addc_u32 s31, s93, 0
	s_add_u32 s34, s92, 0x288d100
	s_addc_u32 s35, s93, 0
	s_add_u32 s36, s92, 0x288d200
	s_addc_u32 s37, s93, 0
	s_add_u32 s38, s92, 0x288d300
	s_mul_i32 s52, s52, s87
	s_addc_u32 s39, s93, 0
	s_mov_b32 s53, 1
	v_mov_b32_e32 v16, 0
	s_branch .LBB0_868

; __device__ __forceinline__ unsigned xb_ld(unsigned* p)              { return __hip_atomic_load(p, __ATOMIC_RELAXED, __HIP_MEMORY_SCOPE_AGENT); }
; __device__ __forceinline__ void xcd_barrier_complete(unsigned* bar, unsigned x, unsigned& nloc, unsigned& nx) {
;     const unsigned G = gridDim.x * gridDim.y * gridDim.z;
;     unsigned sum, cnt, mine, sp = 0u;
;     for (;;) {
;         sum = 0u; cnt = 0u; mine = 0u;
; #pragma unroll
;         for (unsigned j = 0; j < 16; ++j) { const unsigned c = xb_ld(&bar[XB_XCNT(j)]); sum += c; cnt += (c > 0u) ? 1u : 0u; mine = (j == x) ? c : mine; }
; __device__ __forceinline__ void xcd_barrier(const XcdBarrier& b) {
;     asm volatile("s_waitcnt vmcnt(0)" ::: "memory");
;     __syncthreads();
;     if (threadIdx.x == 0) {
;         unsigned* bar = b.bar;
;         __builtin_amdgcn_s_waitcnt(0);
;         unsigned nloc = b.st[0], nx = b.st[1];
;         if (nloc == 0u) { xcd_barrier_complete(bar, b.x, nloc, nx); b.st[0] = nloc; b.st[1] = nx; }
.LBB0_986:
	s_andn2_b64 vcc, exec, s[18:19]
	s_cbranch_vccnz .LBB0_1045
	s_and_b64 s[0:1], s[16:17], s[14:15]
	s_andn2_b64 vcc, exec, s[0:1]
	s_cbranch_vccnz .LBB0_1041
	s_waitcnt vmcnt(0)
	s_waitcnt vmcnt(0) lgkmcnt(0)
	s_barrier
	s_mov_b64 s[0:1], exec
	v_readlane_b32 s2, v247, 1
	v_readlane_b32 s3, v247, 2
	s_and_b64 s[2:3], s[0:1], s[2:3]
	s_mov_b64 exec, s[2:3]
	s_cbranch_execz .LBB0_1040
	s_add_i32 s2, 0, 0x23fc0
	v_mov_b32_e32 v0, s2
	s_waitcnt vmcnt(0) expcnt(0) lgkmcnt(0)
	buffer_inv sc1
	ds_read_b32 v2, v0
	s_add_i32 s2, 0, 0x23fc4
	v_mov_b32_e32 v0, s2
	ds_read_b32 v0, v0
	s_waitcnt lgkmcnt(1)
	v_cmp_ne_u32_e32 vcc, 0, v2
	s_cbranch_vccnz .LBB0_1004
	v_readlane_b32 s2, v247, 0
	s_mul_i32 s33, s2, s86
	s_add_u32 s2, s92, 0x288c200
	s_addc_u32 s3, s93, 0
	s_add_u32 s4, s92, 0x288c400
	s_addc_u32 s5, s93, 0
	s_add_u32 s6, s92, 0x288c500
	s_addc_u32 s7, s93, 0
	s_add_u32 s8, s92, 0x288c600
	s_addc_u32 s9, s93, 0
	s_add_u32 s10, s92, 0x288c700
	s_addc_u32 s11, s93, 0
	s_add_u32 s16, s92, 0x288c800
	s_addc_u32 s17, s93, 0
	s_add_u32 s18, s92, 0x288c900
	s_addc_u32 s19, s93, 0
	s_add_u32 s20, s92, 0x288ca00
	s_addc_u32 s21, s93, 0
	s_add_u32 s22, s92, 0x288cb00
	s_addc_u32 s23, s93, 0
	s_add_u32 s24, s92, 0x288cc00
	s_addc_u32 s25, s93, 0
	s_add_u32 s26, s92, 0x288cd00
	s_addc_u32 s27, s93, 0
	s_add_u32 s28, s92, 0x288ce00
	s_addc_u32 s29, s93, 0
	s_add_u32 s30, s92, 0x288cf00
	s_addc_u32 s31, s93, 0
	s_add_u32 s34, s92, 0x288d000
	s_addc_u32 s35, s93, 0
	s_add_u32 s36, s92, 0x288d100
	s_addc_u32 s37, s93, 0
	s_add_u32 s38, s92, 0x288d200
	s_addc_u32 s39, s93, 0
	s_add_u32 s40, s92, 0x288d300
	s_mul_i32 s33, s33, s87
	s_addc_u32 s41, s93, 0
	s_mov_b32 s48, 1
	v_mov_b32_e32 v16, 0
	s_branch .LBB0_992

; __device__ __forceinline__ unsigned xb_ld(unsigned* p)              { return __hip_atomic_load(p, __ATOMIC_RELAXED, __HIP_MEMORY_SCOPE_AGENT); }
; #define XB_SPIN(cond, bar) do { unsigned _sp = 0; while (cond) { __builtin_amdgcn_s_sleep(1); \
;     if ((++_sp & 255u) == 0u) { if (xb_ld(&(bar)[XB_TMO])) break; if (_sp > XB_SPIN_CAP) { atomicAdd(&(bar)[XB_TMO], 1u); break; } } } } while (0)
; __device__ __forceinline__ void xcd_barrier(const XcdBarrier& b) {
;     ...
;             XB_SPIN(xb_ld(&bar[XB_XGEN(b.x)]) == gen, bar);
;             __builtin_amdgcn_fence(__ATOMIC_ACQUIRE, "agent");
;             asm volatile("s_waitcnt vmcnt(0)" ::: "memory");
.LBB0_1019:
	s_or_b64 exec, exec, s[6:7]
	s_waitcnt vmcnt(0)
	s_waitcnt vmcnt(0)

; __device__ __forceinline__ unsigned xb_ld(unsigned* p)              { return __hip_atomic_load(p, __ATOMIC_RELAXED, __HIP_MEMORY_SCOPE_AGENT); }
; __device__ __forceinline__ unsigned xb_add(unsigned* p, unsigned v) { return __hip_atomic_fetch_add(p, v, __ATOMIC_RELAXED, __HIP_MEMORY_SCOPE_AGENT); }
; #define XB_SPIN(cond, bar) do { unsigned _sp = 0; while (cond) { __builtin_amdgcn_s_sleep(1); \
;     if ((++_sp & 255u) == 0u) { if (xb_ld(&(bar)[XB_TMO])) break; if (_sp > XB_SPIN_CAP) { atomicAdd(&(bar)[XB_TMO], 1u); break; } } } } while (0)
; __device__ __forceinline__ void xcd_barrier(const XcdBarrier& b) {
;     ...
;             else XB_SPIN(xb_ld(&bar[XB_TOPGEN]) == tg, bar);
;             __builtin_amdgcn_fence(__ATOMIC_ACQUIRE, "agent");
;             xb_add(&bar[XB_XGEN(b.x)], 1u);
.LBB0_1037:
	s_or_b64 exec, exec, s[4:5]
	s_mov_b64 s[4:5], exec
	v_mbcnt_lo_u32_b32 v0, s4, 0
	v_mbcnt_hi_u32_b32 v0, s5, v0
	v_cmp_eq_u32_e32 vcc, 0, v0
	s_waitcnt vmcnt(0)
	s_and_saveexec_b64 s[6:7], vcc
	s_cbranch_execz .LBB0_1039
	s_bcnt1_i32_b64 s4, s[4:5]
	v_mov_b32_e32 v0, 0x2000
	v_mov_b32_e32 v1, s4
	global_atomic_add v0, v1, s[2:3] offset:1024
